# RG-LRU item setup (both sweeps): conv-weight, gate-fragment, carry and parameter loads issued together and waited once
# speedup vs baseline: 1.0185x; 1.0088x over previous
.LBB0_316:
	s_and_b32 s4, s33, 7
	s_lshl_b32 s8, s4, 6
	s_waitcnt vmcnt(0)
	s_barrier
	s_mov_b64 s[0:1], exec
	v_readlane_b32 s6, v254, 11
	v_readlane_b32 s7, v254, 12
	s_and_b64 s[6:7], s[0:1], s[6:7]
	s_mov_b64 exec, s[6:7]
	v_or_b32_e32 v0, s8, v151
	v_lshlrev_b32_e32 v0, 2, v0
	v_mov_b32_e32 v1, v32
	v_lshl_add_u64 v[0:1], v[104:105], 0, v[0:1]
	global_load_dword v244, v[0:1], off
	s_mov_b64 exec, s[0:1]
	s_lshl_b32 s0, s10, 4
	s_and_b32 s0, s0, 0x3c000
	v_lshl_or_b32 v0, v193, 4, s0
	v_mov_b32_e32 v1, v32
	v_lshl_add_u64 v[0:1], s[68:69], 0, v[0:1]
	s_mov_b64 s[6:7], 0x2000
	global_load_dwordx4 v[236:239], v[0:1], off
	v_lshl_add_u64 v[0:1], v[0:1], 0, s[6:7]
	global_load_dwordx4 v[240:243], v[0:1], off
	s_bfe_u32 s5, s33, 0x10003
	v_add_u32_e32 v0, s8, v68
	v_lshl_add_u32 v2, s5, 9, v0
	v_ashrrev_i32_e32 v3, 31, v2
	v_lshlrev_b64 v[2:3], 2, v[2:3]
	v_lshl_add_u64 v[4:5], s[40:41], 0, v[2:3]
	global_load_dword v6, v[4:5], off
	v_lshl_add_u64 v[4:5], s[26:27], 0, v[2:3]
	v_lshl_add_u64 v[2:3], s[38:39], 0, v[2:3]
	global_load_dword v1, v[4:5], off
	s_mov_b32 s0, 0x41700000
	global_load_dword v4, v[2:3], off
	s_waitcnt vmcnt(0)
	s_mov_b64 s[0:1], exec
	v_readlane_b32 s6, v254, 11
	v_readlane_b32 s7, v254, 12
	s_and_b64 s[6:7], s[0:1], s[6:7]
	s_mov_b64 exec, s[6:7]
	ds_write_b32 v135, v244
	s_mov_b64 exec, s[0:1]
	ds_write_b128 v152, v[236:239]
	ds_write_b128 v152, v[240:243] offset:8192
	v_readlane_b32 s6, v254, 13
	v_readlane_b32 s7, v254, 14
	s_and_b64 s[6:7], s[0:1], s[6:7]
	s_mov_b64 exec, s[6:7]
	ds_write_b32 v136, v32
	s_mov_b64 exec, s[0:1]
	s_mov_b32 s0, 0x41700000
	v_mul_f32_e32 v2, 0xbfb8aa3b, v6
	v_exp_f32_e32 v5, v2
	v_cmp_nlt_f32_e32 vcc, s0, v6
	s_and_saveexec_b64 s[0:1], vcc
	s_cbranch_execz .LBB0_324
	v_add_f32_e32 v6, 1.0, v5
	v_add_f32_e32 v2, -1.0, v6
	v_sub_f32_e32 v3, v2, v6
	v_add_f32_e32 v3, 1.0, v3
	v_sub_f32_e32 v2, v5, v2
	v_add_f32_e32 v7, v2, v3
	v_frexp_mant_f32_e32 v8, v6
	v_cvt_f64_f32_e32 v[2:3], v6
	s_mov_b32 s6, 0x3f2aaaab
	v_frexp_exp_i32_f64_e32 v2, v[2:3]
	v_cmp_gt_f32_e32 vcc, s6, v8
	s_mov_b32 s6, 0x3f317218
	s_nop 0
	v_subbrev_co_u32_e32 v12, vcc, 0, v2, vcc
	v_sub_u32_e32 v2, 0, v12
	v_ldexp_f32 v3, v6, v2
	v_add_f32_e32 v6, -1.0, v3
	v_add_f32_e32 v8, 1.0, v3
	v_ldexp_f32 v2, v7, v2
	v_add_f32_e32 v7, 1.0, v6
	v_add_f32_e32 v9, -1.0, v8
	v_sub_f32_e32 v7, v3, v7
	v_sub_f32_e32 v3, v3, v9
	v_add_f32_e32 v7, v2, v7
	v_add_f32_e32 v2, v2, v3
	v_add_f32_e32 v13, v8, v2
	v_rcp_f32_e32 v15, v13
	v_sub_f32_e32 v3, v13, v8
	v_sub_f32_e32 v14, v2, v3
	v_add_f32_e32 v3, v6, v7
	v_mul_f32_e32 v17, v3, v15
	v_sub_f32_e32 v2, v3, v6
	v_mul_f32_e32 v6, v13, v17
	v_fma_f32 v8, v17, v13, -v6
	v_fmac_f32_e32 v8, v17, v14
	v_sub_f32_e32 v16, v7, v2
	v_add_f32_e32 v2, v6, v8
	v_sub_f32_e32 v7, v3, v2
	v_pk_add_f32 v[10:11], v[2:3], v[6:7] neg_lo:[0,1] neg_hi:[0,1]
	v_mov_b32_e32 v9, v2
	v_pk_add_f32 v[2:3], v[10:11], v[8:9] neg_lo:[0,1] neg_hi:[0,1]
	s_nop 0
	v_add_f32_e32 v3, v16, v3
	v_add_f32_e32 v2, v2, v3
	v_add_f32_e32 v3, v7, v2
	v_mul_f32_e32 v16, v15, v3
	v_mul_f32_e32 v6, v13, v16
	v_fma_f32 v8, v16, v13, -v6
	v_fmac_f32_e32 v8, v16, v14
	v_sub_f32_e32 v7, v7, v3
	v_add_f32_e32 v13, v2, v7
	v_add_f32_e32 v2, v6, v8
	v_sub_f32_e32 v7, v3, v2
	v_pk_add_f32 v[10:11], v[2:3], v[6:7] neg_lo:[0,1] neg_hi:[0,1]
	v_mov_b32_e32 v9, v2
	v_pk_add_f32 v[2:3], v[10:11], v[8:9] neg_lo:[0,1] neg_hi:[0,1]
	s_nop 0
	v_add_f32_e32 v3, v13, v3
	v_add_f32_e32 v2, v2, v3
	v_add_f32_e32 v3, v17, v16
	v_add_f32_e32 v2, v7, v2
	v_sub_f32_e32 v6, v3, v17
	v_mul_f32_e32 v2, v15, v2
	v_sub_f32_e32 v6, v16, v6
	v_add_f32_e32 v6, v6, v2
	v_add_f32_e32 v8, v3, v6
	v_mul_f32_e32 v9, v8, v8
	v_fmamk_f32 v2, v9, 0x3e9b6dac, v154
	v_fmaak_f32 v107, v9, v2, 0x3f2aaada
	v_cvt_f32_i32_e32 v2, v12
	v_sub_f32_e32 v3, v8, v3
	v_sub_f32_e32 v3, v6, v3
	v_ldexp_f32 v10, v3, 1
	v_mul_f32_e32 v3, v8, v9
	v_ldexp_f32 v7, v8, 1
	v_pk_mul_f32 v[8:9], v[2:3], v[106:107]
	s_nop 0
	v_fma_f32 v6, v2, s6, -v8
	v_fmac_f32_e32 v6, 0xb102e308, v2
	v_pk_add_f32 v[2:3], v[8:9], v[6:7]
	s_mov_b32 s6, 0x7f800000
	v_sub_f32_e32 v7, v3, v7
	v_sub_f32_e32 v7, v9, v7
	v_add_f32_e32 v11, v10, v7
	v_mov_b32_e32 v10, v8
	v_pk_add_f32 v[8:9], v[2:3], v[8:9] neg_lo:[0,1] neg_hi:[0,1]
	v_pk_add_f32 v[12:13], v[2:3], v[10:11]
	v_mov_b32_e32 v7, v2
	v_mov_b32_e32 v9, v13
	v_pk_add_f32 v[14:15], v[6:7], v[8:9] neg_lo:[0,1] neg_hi:[0,1]
	v_pk_add_f32 v[6:7], v[6:7], v[8:9]
	v_mov_b32_e32 v10, v11
	v_pk_add_f32 v[8:9], v[6:7], v[2:3] op_sel:[1,0] op_sel_hi:[0,1] neg_lo:[0,1] neg_hi:[0,1]
	v_pk_add_f32 v[16:17], v[12:13], v[8:9] op_sel_hi:[1,0] neg_lo:[0,1] neg_hi:[0,1]
	v_mov_b32_e32 v12, v13
	v_mov_b32_e32 v13, v7
	v_pk_mov_b32 v[8:9], v[2:3], v[8:9] op_sel:[1,0]
	v_mov_b32_e32 v11, v2
	v_pk_add_f32 v[8:9], v[12:13], v[8:9] neg_lo:[0,1] neg_hi:[0,1]
	v_mov_b32_e32 v16, v14
	v_pk_add_f32 v[2:3], v[10:11], v[8:9] neg_lo:[0,1] neg_hi:[0,1]
	v_mov_b32_e32 v15, v7
	v_pk_add_f32 v[8:9], v[16:17], v[2:3]
	v_cmp_neq_f32_e32 vcc, s6, v5
	v_pk_add_f32 v[10:11], v[8:9], v[8:9] op_sel:[0,1] op_sel_hi:[1,0]
	s_mov_b32 s6, 0x33800000
	v_pk_add_f32 v[6:7], v[6:7], v[10:11] op_sel:[1,0] op_sel_hi:[0,1]
	v_mov_b32_e32 v9, v6
	v_pk_add_f32 v[12:13], v[8:9], v[14:15] neg_lo:[0,1] neg_hi:[0,1]
	v_mov_b32_e32 v3, v10
	v_sub_f32_e32 v7, v8, v12
	v_pk_add_f32 v[2:3], v[2:3], v[12:13] neg_lo:[0,1] neg_hi:[0,1]
	v_sub_f32_e32 v7, v14, v7
	v_add_f32_e32 v2, v2, v7
	v_add_f32_e32 v2, v2, v3
	v_add_f32_e32 v2, v6, v2
	v_cndmask_b32_e32 v2, v158, v2, vcc
	v_cmp_ngt_f32_e32 vcc, -1.0, v5
	s_nop 1
	v_cndmask_b32_e32 v2, v159, v2, vcc
	v_cmp_neq_f32_e32 vcc, -1.0, v5
	s_nop 1
	v_cndmask_b32_e32 v2, v160, v2, vcc
	v_cmp_lt_f32_e64 vcc, |v5|, s6
	s_nop 1
	v_cndmask_b32_e32 v5, v2, v5, vcc

.LBB0_553:
	s_and_b32 s48, s64, 7
	s_lshl_b32 s11, s48, 6
	s_barrier
	s_and_saveexec_b64 s[8:9], s[2:3]
	v_or_b32_e32 v0, s11, v141
	v_lshlrev_b32_e32 v0, 2, v0
	v_mov_b32_e32 v1, v32
	v_lshl_add_u64 v[0:1], v[78:79], 0, v[0:1]
	global_load_dword v244, v[0:1], off
	s_or_b64 exec, exec, s[8:9]
	s_lshr_b32 s10, s64, 3
	s_bitcmp1_b32 s64, 3
	s_cselect_b64 s[8:9], -1, 0
	s_xor_b64 s[8:9], s[8:9], -1
	v_cndmask_b32_e64 v0, 0, 1, s[8:9]
	s_and_b32 s8, s63, 7
	v_lshl_or_b32 v0, v0, 17, v103
	v_lshl_or_b32 v0, s8, 14, v0
	v_mov_b32_e32 v1, v32
	v_lshl_add_u64 v[0:1], s[20:21], 0, v[0:1]
	global_load_dwordx4 v[236:239], v[0:1], off
	v_lshl_add_u64 v[0:1], v[0:1], 0, s[22:23]
	global_load_dwordx4 v[240:243], v[0:1], off
	s_and_b32 s10, s10, 1
	s_xor_b32 s49, s10, 1
	s_and_saveexec_b64 s[8:9], s[4:5]
	s_lshl_b32 s48, s48, 1
	s_and_b32 s50, s64, -16
	s_or_b32 s48, s48, s50
	s_or_b32 s50, s48, s49
	s_ashr_i32 s51, s50, 31
	s_lshl_b64 s[50:51], s[50:51], 8
	v_lshl_add_u64 v[0:1], v[76:77], 0, s[50:51]
	global_load_dword v245, v[0:1], off
	s_or_b64 exec, exec, s[8:9]
	v_add_u32_e32 v0, s11, v102
	v_lshl_add_u32 v2, s49, 9, v0
	v_ashrrev_i32_e32 v3, 31, v2
	v_lshlrev_b64 v[2:3], 2, v[2:3]
	v_lshl_add_u64 v[4:5], s[40:41], 0, v[2:3]
	global_load_dword v6, v[4:5], off
	v_lshl_add_u64 v[4:5], s[26:27], 0, v[2:3]
	v_lshl_add_u64 v[2:3], s[38:39], 0, v[2:3]
	global_load_dword v1, v[4:5], off
	global_load_dword v2, v[2:3], off
	s_waitcnt vmcnt(0)
	s_and_saveexec_b64 s[8:9], s[2:3]
	ds_write_b32 v105, v244
	s_or_b64 exec, exec, s[8:9]
	ds_write_b128 v142, v[236:239]
	ds_write_b128 v142, v[240:243] offset:8192
	s_and_saveexec_b64 s[8:9], s[4:5]
	ds_write_b32 v106, v245
	s_or_b64 exec, exec, s[8:9]
	v_cmp_nlt_f32_e32 vcc, s24, v6
	v_mul_f32_e32 v3, 0xbfb8aa3b, v6
	v_exp_f32_e32 v3, v3
	s_and_saveexec_b64 s[8:9], vcc
	s_cbranch_execz .LBB0_561
	v_add_f32_e32 v6, 1.0, v3
	v_add_f32_e32 v4, -1.0, v6
	v_sub_f32_e32 v5, v4, v6
	v_add_f32_e32 v5, 1.0, v5
	v_sub_f32_e32 v4, v3, v4
	v_add_f32_e32 v7, v4, v5
	v_frexp_mant_f32_e32 v8, v6
	v_cvt_f64_f32_e32 v[4:5], v6
	v_frexp_exp_i32_f64_e32 v4, v[4:5]
	v_cmp_gt_f32_e32 vcc, s25, v8
	s_nop 1
	v_subbrev_co_u32_e32 v12, vcc, 0, v4, vcc
	v_sub_u32_e32 v4, 0, v12
	v_ldexp_f32 v5, v6, v4
	v_add_f32_e32 v6, -1.0, v5
	v_add_f32_e32 v8, 1.0, v5
	v_ldexp_f32 v4, v7, v4
	v_add_f32_e32 v7, 1.0, v6
	v_add_f32_e32 v9, -1.0, v8
	v_sub_f32_e32 v7, v5, v7
	v_sub_f32_e32 v5, v5, v9
	v_add_f32_e32 v7, v4, v7
	v_add_f32_e32 v4, v4, v5
	v_add_f32_e32 v13, v8, v4
	v_rcp_f32_e32 v15, v13
	v_sub_f32_e32 v5, v13, v8
	v_sub_f32_e32 v14, v4, v5
	v_add_f32_e32 v5, v6, v7
	v_mul_f32_e32 v17, v5, v15
	v_sub_f32_e32 v4, v5, v6
	v_mul_f32_e32 v6, v13, v17
	v_fma_f32 v8, v17, v13, -v6
	v_fmac_f32_e32 v8, v17, v14
	v_sub_f32_e32 v16, v7, v4
	v_add_f32_e32 v4, v6, v8
	v_sub_f32_e32 v7, v5, v4
	v_pk_add_f32 v[10:11], v[4:5], v[6:7] neg_lo:[0,1] neg_hi:[0,1]
	v_mov_b32_e32 v9, v4
	v_pk_add_f32 v[4:5], v[10:11], v[8:9] neg_lo:[0,1] neg_hi:[0,1]
	v_cmp_neq_f32_e32 vcc, s31, v3
	v_add_f32_e32 v5, v16, v5
	v_add_f32_e32 v4, v4, v5
	v_add_f32_e32 v5, v7, v4
	v_mul_f32_e32 v16, v15, v5
	v_mul_f32_e32 v6, v13, v16
	v_fma_f32 v8, v16, v13, -v6
	v_fmac_f32_e32 v8, v16, v14
	v_sub_f32_e32 v7, v7, v5
	v_add_f32_e32 v13, v4, v7
	v_add_f32_e32 v4, v6, v8
	v_sub_f32_e32 v7, v5, v4
	v_pk_add_f32 v[10:11], v[4:5], v[6:7] neg_lo:[0,1] neg_hi:[0,1]
	v_mov_b32_e32 v9, v4
	v_pk_add_f32 v[4:5], v[10:11], v[8:9] neg_lo:[0,1] neg_hi:[0,1]
	s_nop 0
	v_add_f32_e32 v5, v13, v5
	v_add_f32_e32 v4, v4, v5
	v_add_f32_e32 v5, v17, v16
	v_add_f32_e32 v4, v7, v4
	v_sub_f32_e32 v6, v5, v17
	v_mul_f32_e32 v4, v15, v4
	v_sub_f32_e32 v6, v16, v6
	v_add_f32_e32 v6, v6, v4
	v_add_f32_e32 v8, v5, v6
	v_mul_f32_e32 v9, v8, v8
	v_fmamk_f32 v4, v9, 0x3e9b6dac, v144
	v_fmaak_f32 v81, v9, v4, 0x3f2aaada
	v_cvt_f32_i32_e32 v4, v12
	v_sub_f32_e32 v5, v8, v5
	v_sub_f32_e32 v5, v6, v5
	v_ldexp_f32 v10, v5, 1
	v_mul_f32_e32 v5, v8, v9
	v_ldexp_f32 v7, v8, 1
	v_pk_mul_f32 v[8:9], v[4:5], v[80:81]
	s_nop 0
	v_fma_f32 v6, v4, s30, -v8
	v_fmac_f32_e32 v6, 0xb102e308, v4
	v_pk_add_f32 v[4:5], v[8:9], v[6:7]
	s_nop 0
	v_sub_f32_e32 v7, v5, v7
	v_sub_f32_e32 v7, v9, v7
	v_add_f32_e32 v11, v10, v7
	v_mov_b32_e32 v10, v8
	v_pk_add_f32 v[8:9], v[4:5], v[8:9] neg_lo:[0,1] neg_hi:[0,1]
	v_pk_add_f32 v[12:13], v[4:5], v[10:11]
	v_mov_b32_e32 v7, v4
	v_mov_b32_e32 v9, v13
	v_pk_add_f32 v[14:15], v[6:7], v[8:9] neg_lo:[0,1] neg_hi:[0,1]
	v_pk_add_f32 v[6:7], v[6:7], v[8:9]
	v_mov_b32_e32 v10, v11
	v_pk_add_f32 v[8:9], v[6:7], v[4:5] op_sel:[1,0] op_sel_hi:[0,1] neg_lo:[0,1] neg_hi:[0,1]
	v_pk_add_f32 v[16:17], v[12:13], v[8:9] op_sel_hi:[1,0] neg_lo:[0,1] neg_hi:[0,1]
	v_mov_b32_e32 v12, v13
	v_mov_b32_e32 v13, v7
	v_pk_mov_b32 v[8:9], v[4:5], v[8:9] op_sel:[1,0]
	v_mov_b32_e32 v11, v4
	v_pk_add_f32 v[8:9], v[12:13], v[8:9] neg_lo:[0,1] neg_hi:[0,1]
	v_mov_b32_e32 v16, v14
	v_pk_add_f32 v[4:5], v[10:11], v[8:9] neg_lo:[0,1] neg_hi:[0,1]
	v_mov_b32_e32 v15, v7
	v_pk_add_f32 v[8:9], v[16:17], v[4:5]
	s_nop 0
	v_pk_add_f32 v[10:11], v[8:9], v[8:9] op_sel:[0,1] op_sel_hi:[1,0]
	s_nop 0
	v_pk_add_f32 v[6:7], v[6:7], v[10:11] op_sel:[1,0] op_sel_hi:[0,1]
	v_mov_b32_e32 v9, v6
	v_pk_add_f32 v[12:13], v[8:9], v[14:15] neg_lo:[0,1] neg_hi:[0,1]
	v_mov_b32_e32 v5, v10
	v_sub_f32_e32 v7, v8, v12
	v_pk_add_f32 v[4:5], v[4:5], v[12:13] neg_lo:[0,1] neg_hi:[0,1]
	v_sub_f32_e32 v7, v14, v7
	v_add_f32_e32 v4, v4, v7
	v_add_f32_e32 v4, v4, v5
	v_add_f32_e32 v4, v6, v4
	v_cndmask_b32_e32 v4, v149, v4, vcc
	v_cmp_ngt_f32_e32 vcc, -1.0, v3
	s_nop 1
	v_cndmask_b32_e32 v4, v150, v4, vcc
	v_cmp_neq_f32_e32 vcc, -1.0, v3
	s_nop 1
	v_cndmask_b32_e32 v4, v151, v4, vcc
	v_cmp_lt_f32_e64 vcc, |v3|, s33
	s_nop 1
	v_cndmask_b32_e32 v3, v4, v3, vcc
